# strategy 4 mirror: static s_setprio 1 for waves 0-3 (older half) during the chunk-prep loop
# baseline (speedup 1.0000x reference)
.LBB0_268:
	v_mov_b32_e32 v141, 0
	v_lshlrev_b32_e32 v140, 4, v94
	v_lshl_add_u64 v[98:99], s[70:71], 0, v[140:141]
	s_mov_b64 s[6:7], 0x7600000
	v_lshl_add_u32 v133, v1, 15, 0
	v_lshlrev_b32_e32 v96, 2, v131
	v_lshl_add_u64 v[142:143], v[98:99], 0, s[6:7]
	s_mov_b64 s[6:7], 0x7630000
	v_add_u32_e32 v135, v133, v96
	v_lshlrev_b32_e32 v136, 4, v95
	v_lshl_add_u64 v[144:145], v[98:99], 0, s[6:7]
	s_mov_b64 s[6:7], 0x7660000
	v_sub_u32_e32 v97, v135, v136
	v_lshl_add_u64 v[146:147], v[98:99], 0, s[6:7]
	v_mul_u32_u24_e32 v98, 0x48, v134
	v_lshl_add_u32 v165, v98, 1, v97
	v_mov_b32_e32 v97, v141
	v_bfe_u32 v100, v0, 6, 1
	v_lshl_add_u64 v[96:97], s[70:71], 0, v[96:97]
	s_mov_b64 s[14:15], 0x15a08000
	v_add_u32_e32 v101, 0x1b00, v133
	v_cmp_gt_u32_e64 s[8:9], 64, v4
	v_lshl_add_u32 v161, v4, 2, v133
	v_cmp_gt_u32_e64 s[10:11], 8, v4
	v_lshl_add_u64 v[154:155], v[96:97], 0, s[14:15]
	v_and_b32_e32 v4, 64, v0
	v_cmp_eq_u32_e32 vcc, 0, v100
	v_mul_u32_u24_e32 v96, 0x48, v132
	v_lshl_or_b32 v149, v100, 5, v132
	v_lshl_add_u64 v[156:157], s[12:13], 0, v[140:141]
	v_cmp_ne_u32_e64 s[12:13], 0, v4
	v_cndmask_b32_e32 v4, v101, v133, vcc
	v_lshlrev_b32_e32 v99, 1, v96
	v_lshlrev_b32_e32 v96, 1, v132
	v_mov_b32_e32 v97, v141
	v_lshlrev_b32_e32 v148, 2, v94
	v_add3_u32 v167, v4, v99, v140
	v_add_u32_e32 v101, v133, v96
	v_lshl_add_u64 v[158:159], s[68:69], 0, v[96:97]
	v_cmp_gt_u32_e64 s[14:15], 32, v3
	v_add_u32_e32 v97, v133, v140
	v_lshrrev_b32_e32 v160, 2, v3
	v_lshlrev_b32_e32 v140, 1, v3
	v_lshlrev_b32_e32 v3, 2, v149
	v_add_u32_e32 v102, v101, v96
	v_lshl_or_b32 v96, v94, 10, v3
	v_or_b32_e32 v164, 1, v148
	v_add_u32_e32 v169, v133, v96
	v_lshl_or_b32 v96, v164, 8, v3
	v_or_b32_e32 v166, 2, v148
	v_add_u32_e32 v171, v133, v96
	v_lshl_or_b32 v96, v166, 8, v3
	v_cmp_lt_u32_e64 s[20:21], v132, v166
	v_add_u32_e32 v194, v133, v96
	v_or_b32_e32 v168, 3, v148
	v_cndmask_b32_e64 v96, 0, 1, s[20:21]
	v_cmp_le_u32_e64 s[20:21], v132, v166
	s_add_u32 s30, s70, 0x7900000
	v_lshl_or_b32 v3, v168, 8, v3
	v_add_u32_e32 v199, v97, v99
	v_cndmask_b32_e64 v99, 0, 1, s[20:21]
	s_addc_u32 s31, s71, 0
	v_add_u32_e32 v195, v133, v3
	v_mul_u32_u24_e32 v3, 0xc0, v95
	v_cndmask_b32_e32 v96, v99, v96, vcc
	s_add_u32 s42, s70, 0x9900000
	v_lshlrev_b32_e32 v150, 1, v134
	v_lshlrev_b32_e32 v3, 1, v3
	v_cmp_lt_u32_e64 s[16:17], v132, v148
	v_and_b32_e32 v96, 1, v96
	v_cmp_lt_u32_e64 s[22:23], v132, v168
	s_addc_u32 s43, s71, 0
	s_waitcnt lgkmcnt(0)
	s_load_dword s3, s[0:1], 0xd8
	v_add3_u32 v197, v133, v150, v3
	v_add3_u32 v198, v133, v3, v150
	v_cndmask_b32_e64 v3, 0, 1, s[16:17]
	v_cmp_le_u32_e64 s[16:17], v132, v148
	v_cmp_eq_u32_e64 s[20:21], 1, v96
	v_cndmask_b32_e64 v96, 0, 1, s[22:23]
	v_cmp_le_u32_e64 s[22:23], v132, v168
	s_add_u32 s46, s70, 0x15c08000
	v_cmp_eq_u32_e64 s[6:7], 0, v95
	v_lshlrev_b32_e32 v152, 1, v95
	v_cndmask_b32_e64 v95, 0, 1, s[16:17]
	v_cndmask_b32_e64 v99, 0, 1, s[22:23]
	s_addc_u32 s47, s71, 0
	s_movk_i32 s24, 0x210
	v_cndmask_b32_e32 v3, v95, v3, vcc
	v_cndmask_b32_e32 v96, v99, v96, vcc
	s_add_u32 s50, s70, 0xb900000
	v_and_b32_e32 v3, 1, v3
	v_and_b32_e32 v96, 1, v96
	s_movk_i32 s25, 0x840
	v_mad_u32_u24 v108, v164, s24, v133
	s_addc_u32 s51, s71, 0
	v_cmp_eq_u32_e64 s[16:17], 1, v3
	v_mul_u32_u24_e32 v3, 0x110, v94
	v_or_b32_e32 v95, v148, v100
	v_cmp_eq_u32_e64 s[22:23], 1, v96
	v_lshl_or_b32 v99, v100, 1, 1
	v_lshlrev_b32_e32 v96, 4, v100
	v_mul_u32_u24_e32 v104, 0xc0, v94
	v_lshlrev_b32_e32 v100, 7, v100
	v_mad_u32_u24 v94, v94, s25, v133
	v_lshlrev_b32_e32 v107, 2, v132
	v_add_u32_e32 v109, 0x210, v108
	v_add_u32_e32 v110, 0x420, v108
	s_waitcnt lgkmcnt(0)
	s_cmpk_lg_i32 s3, 0x100
	v_lshlrev_b32_e32 v4, 4, v0
	v_add3_u32 v200, v94, v100, v107
	v_add3_u32 v201, v108, v100, v107
	v_add3_u32 v202, v109, v100, v107
	v_add3_u32 v203, v110, v100, v107
	v_lshl_or_b32 v100, v99, 4, v132
	s_cselect_b64 s[52:53], -1, 0
	v_mul_u32_u24_e32 v98, 0x210, v134
	v_mul_u32_u24_e32 v103, 48, v132
	v_and_b32_e32 v4, 48, v4
	v_cmp_gt_u32_e64 s[18:19], v132, v95
	v_mul_u32_u24_e32 v95, 0x44, v164
	v_mul_u32_u24_e32 v105, 48, v164
	v_mul_u32_u24_e32 v106, 48, v149
	v_mul_u32_u24_e32 v100, 48, v100
	v_lshlrev_b32_e32 v99, 6, v99
	s_lshl_b32 s64, s3, 2
	v_lshl_add_u32 v153, v134, 8, v135
	v_mov_b32_e32 v137, v141
	v_mov_b32_e32 v151, v141
	v_lshl_add_u64 v[162:163], s[30:31], 0, v[140:141]
	v_or_b32_e32 v196, 16, v149
	v_or_b32_e32 v170, 1, v152
	v_add3_u32 v204, v94, v99, v107
	v_add3_u32 v205, v108, v99, v107
	v_add3_u32 v206, v109, v99, v107
	v_add3_u32 v207, v110, v99, v107
	s_lshl_b32 s65, s2, 2
	v_or_b32_e32 v208, s64, v1
	s_movk_i32 s66, 0xff0
	s_mov_b32 s67, 0xbfb8aa3b
	s_mov_b32 s74, 0x800000
	s_mov_b32 s75, 0x3f317217
	s_mov_b32 s76, 0x7f800000
	s_mov_b32 s77, 0xf800000
	v_mov_b32_e32 v209, 0x260
	v_add_u32_e32 v210, v135, v98
	s_movk_i32 s78, 0x3c0
	s_movk_i32 s79, 0x1800
	s_movk_i32 s80, 0x1000
	v_add_u32_e32 v211, v102, v3
	v_lshlrev_b32_e32 v172, 1, v96
	v_add_u32_e32 v212, v101, v104
	v_add_u32_e32 v213, v97, v106
	v_add_u32_e32 v214, v97, v100
	v_lshlrev_b32_e32 v174, 1, v4
	v_mov_b32_e32 v215, 0x41b17218
	v_add_u32_e32 v216, v102, v95
	v_add_u32_e32 v217, v101, v105
	v_add_u32_e32 v218, v97, v103
	s_mov_b32 s81, s2
	v_readfirstlane_b32 vcc_lo, v0
	s_nop 1
	s_lshr_b32 vcc_lo, vcc_lo, 6
	s_cmp_lt_u32 vcc_lo, 4
	s_cbranch_scc0 .Lprep_sh
	s_setprio 1
	s_branch .Lprep_in
.Lprep_sh:
	s_barrier
	s_barrier
	s_barrier

.Lat_pv_done:
	s_nop 7
	v_cvt_pk_bf16_f32 v22, v240, v240
	v_cvt_pk_bf16_f32 v23, v241, v241
	v_cvt_pk_bf16_f32 v24, v242, v242
	v_cvt_pk_bf16_f32 v25, v243, v243
	v_cvt_pk_bf16_f32 v26, v244, v244
	v_cvt_pk_bf16_f32 v27, v245, v245
	v_cvt_pk_bf16_f32 v28, v246, v246
	v_cvt_pk_bf16_f32 v29, v247, v247
	v_cvt_pk_bf16_f32 v134, v248, v248
	v_cvt_pk_bf16_f32 v135, v249, v249
	v_cvt_pk_bf16_f32 v136, v250, v250
	v_cvt_pk_bf16_f32 v137, v251, v251
	v_cvt_pk_bf16_f32 v138, v120, v120
	v_cvt_pk_bf16_f32 v139, v121, v121
	v_cvt_pk_bf16_f32 v150, v122, v122
	v_cvt_pk_bf16_f32 v151, v123, v123
	global_store_short v17, v22, s[20:21]
	global_store_short v17, v23, s[20:21] offset:2048
	global_store_short v18, v24, s[20:21]
	global_store_short v18, v25, s[20:21] offset:2048
	global_store_short v17, v26, s[20:21] offset:32
	global_store_short v17, v27, s[20:21] offset:2080
	global_store_short v18, v28, s[20:21] offset:32
	global_store_short v18, v29, s[20:21] offset:2080
	global_store_short v17, v134, s[20:21] offset:64
	global_store_short v17, v135, s[20:21] offset:2112
	global_store_short v18, v136, s[20:21] offset:64
	global_store_short v18, v137, s[20:21] offset:2112
	global_store_short v17, v138, s[20:21] offset:96
	global_store_short v17, v139, s[20:21] offset:2144
	global_store_short v18, v150, s[20:21] offset:96
	global_store_short v18, v151, s[20:21] offset:2144
	s_add_u32 s3, s3, s6
	s_cmp_lt_u32 s3, 0x2000
	s_cbranch_scc1 .Lat_loop
	v_and_b32_e32 v10, 15, v0
	s_add_u32 s74, s0, 0xd8
	s_addc_u32 s75, s1, 0
	v_mov_b64_e32 v[2:3], s[74:75]
	s_mov_b64 s[64:65], exec
	s_nop 0
	s_nop 0
	s_nop 0
	s_nop 0
	s_nop 0
	s_nop 0
	s_nop 0
	s_nop 0
	s_nop 0
	s_nop 0
	s_nop 0
	s_nop 0
	s_nop 0
	s_nop 0
.LBB0_388:
	s_or_b64 exec, exec, s[64:65]
	s_sub_i32 s6, s2, 32
	v_readfirstlane_b32 s7, v0
	s_cmpk_gt_u32 s6, 0x17f
	v_lshlrev_b32_e32 v157, 2, v0
	s_waitcnt lgkmcnt(0)
	s_barrier
	s_cbranch_scc1 .LBB0_405
	v_lshrrev_b32_e32 v1, 5, v0
	global_load_dword v15, v[2:3], off
	v_and_b32_e32 v2, 4, v1
	v_lshrrev_b32_e32 v1, 1, v0
	v_bfe_u32 v3, v0, 2, 2
	v_and_b32_e32 v1, 24, v1
	s_add_u32 s8, s70, 0x10900000
	v_or3_b32 v2, v2, v3, v1
	v_lshlrev_b32_e32 v3, 4, v0
	s_addc_u32 s9, s71, 0
	v_or_b32_e32 v11, 0x2000, v3
	s_add_u32 s10, s70, 0x2e00000
	v_lshrrev_b32_e32 v4, 7, v11
	s_movk_i32 s3, 0x60
	s_waitcnt vmcnt(18)
	v_bfe_u32 v14, v0, 2, 4
	s_movk_i32 s12, 0x70
	s_addc_u32 s11, s71, 0
	v_and_or_b32 v5, v4, s3, v2
	v_and_or_b32 v4, v4, s12, v14
	s_and_b32 s12, s2, 7
	s_lshr_b32 s13, s6, 3
	s_mul_i32 s12, s12, 48
	s_add_i32 s12, s12, s13
	s_mul_i32 s13, s12, 0xaaab
	s_lshr_b32 s13, s13, 22
	s_lshl_b32 s14, s13, 3
	s_mulk_i32 s13, 0x60
	s_sub_i32 s12, s12, s13
	s_and_b32 s13, s12, 7
	v_and_b32_e32 v6, 32, v0
	s_or_b32 s18, s14, s13
	s_lshr_b32 s22, s7, 6
	v_bitop3_b32 v12, v3, v6, 48 bitop3:0x6c
	v_and_b32_e32 v13, 64, v0
	s_bfe_u32 s19, s12, 0x50003
	s_and_b32 s12, s18, 0x1fff
	s_mov_b32 s13, 0
	s_lshr_b32 s24, s7, 8
	s_lshl_b32 s42, s22, 10
	v_or_b32_e32 v3, v12, v13
	s_lshl_b64 s[14:15], s[12:13], 20
	s_lshl_b32 s12, s19, 20
	v_lshl_or_b32 v134, v4, 12, v3
	v_lshrrev_b32_e32 v4, 3, v0
	s_add_u32 s30, s10, s12
	v_and_or_b32 v2, v4, 32, v2
	s_addc_u32 s31, s11, 0
	s_add_i32 s12, s42, 0
	v_lshl_or_b32 v136, v2, 12, v3
	s_add_i32 m0, s12, 0x10000
	v_lshl_or_b32 v132, v5, 12, v3
	global_load_lds_dwordx4 v136, s[30:31]
	s_add_i32 m0, s12, 0x12000
	s_add_u32 s16, s30, 0x80000
	global_load_lds_dwordx4 v132, s[30:31]
	s_addc_u32 s17, s31, 0
	s_add_i32 m0, s12, 0x14000
	v_and_or_b32 v2, v4, 48, v14
	global_load_lds_dwordx4 v136, s[16:17]
	s_add_i32 m0, s12, 0x16000
	s_add_u32 s44, s8, s14
	s_addc_u32 s45, s9, s15
	s_add_i32 s78, s12, 0x2000
	v_lshl_or_b32 v138, v2, 12, v3
	global_load_lds_dwordx4 v132, s[16:17]
	s_mov_b32 m0, s12
	s_add_u32 s14, s44, 0x80000
	global_load_lds_dwordx4 v138, s[44:45]
	s_mov_b32 m0, s78
	s_addc_u32 s15, s45, 0
	s_add_i32 s79, s12, 0x4000
	global_load_lds_dwordx4 v134, s[44:45]
	s_mov_b32 m0, s79
	s_add_i32 s80, s12, 0x6000
	global_load_lds_dwordx4 v138, s[14:15]
	s_mov_b32 m0, s80
	v_mov_b32_e32 v137, 0
	global_load_lds_dwordx4 v134, s[14:15]
	v_mov_b32_e32 v133, v137
	v_mov_b32_e32 v139, v137
	v_mov_b32_e32 v135, v137
	s_cmp_eq_u32 s24, 1
	v_lshl_add_u64 v[8:9], s[30:31], 0, v[136:137]
	v_lshl_add_u64 v[4:5], s[30:31], 0, v[132:133]
	s_mov_b64 s[14:15], 0x80000
	v_lshl_add_u64 v[2:3], s[44:45], 0, v[138:139]
	s_cselect_b64 s[16:17], -1, 0
	s_cmp_lg_u32 s24, 1
	v_lshl_add_u64 v[6:7], s[44:45], 0, v[134:135]
	s_cbranch_scc1 .LBB0_391
	s_barrier
